# scan interval B: prefetch next group's transposed k reads before current group's MFMAs (groups 0-4, double-buffered fragments)
# baseline (speedup 1.0000x reference)
.LBB0_617:
	ds_read_b128 v[164:167], v190
	ds_read_b64_tr_b16 v[126:127], v189 offset:576
	ds_read_b64_tr_b16 v[122:123], v189 offset:5184
	ds_read_b64_tr_b16 v[124:125], v189
	ds_read_b64_tr_b16 v[120:121], v189 offset:4608
	ds_read_b128 v[168:171], v190 offset:2304
	ds_read_b128 v[176:179], v190 offset:4608
	ds_read_b128 v[202:205], v190 offset:6912
	s_waitcnt lgkmcnt(5)
	v_cndmask_b32_e64 v175, v123, v127, s[4:5]
	v_cndmask_b32_e64 v174, v122, v126, s[4:5]
	s_waitcnt lgkmcnt(3)
	v_cndmask_b32_e64 v173, v121, v125, s[4:5]
	v_cndmask_b32_e64 v172, v120, v124, s[4:5]
	s_add_i32 s27, s22, -3
	s_min_u32 s8, s27, 61
	v_mfma_f32_16x16x32_bf16 v[164:167], v[164:167], v[172:175], 0
	s_lshl_b32 s8, s8, 6
	s_addk_i32 s8, 0x80
	s_waitcnt lgkmcnt(2)
	v_mfma_f32_16x16x32_bf16 v[168:171], v[168:171], v[172:175], 0
	s_waitcnt lgkmcnt(1)
	v_mfma_f32_16x16x32_bf16 v[176:179], v[176:179], v[172:175], 0
	s_waitcnt lgkmcnt(0)
	v_mfma_f32_16x16x32_bf16 v[172:175], v[202:205], v[172:175], 0
	s_waitcnt vmcnt(21)
	ds_write_b128 v191, v[0:3] offset:33792
	v_lshl_add_u64 v[0:1], s[8:9], 0, v[134:135]
	v_lshlrev_b64 v[0:1], 11, v[0:1]
	v_lshl_add_u64 v[0:1], v[146:147], 0, v[0:1]
	global_load_dwordx4 v[0:3], v[0:1], off
	ds_read_b128 v[202:205], v192
	ds_read_b128 v[206:209], v192 offset:8448
	v_cvt_pk_bf16_f32 v210, v88, v89
	v_cvt_pk_bf16_f32 v211, v90, v91
	v_cvt_pk_bf16_f32 v212, v92, v93
	v_cvt_pk_bf16_f32 v213, v94, v95
	s_waitcnt lgkmcnt(1)
	s_nop 0
	v_mfma_f32_16x16x32_bf16 v[164:167], v[202:205], v[210:213], v[164:167]
	ds_read_b128 v[202:205], v192 offset:16896
	s_waitcnt lgkmcnt(1)
	v_mfma_f32_16x16x32_bf16 v[168:171], v[206:209], v[210:213], v[168:171]
	ds_read_b128 v[206:209], v192 offset:25344
	s_waitcnt lgkmcnt(1)
	v_mfma_f32_16x16x32_bf16 v[176:179], v[202:205], v[210:213], v[176:179]
	s_waitcnt lgkmcnt(0)
	v_mfma_f32_16x16x32_bf16 v[172:175], v[206:209], v[210:213], v[172:175]
	s_waitcnt vmcnt(21)
	ds_write_b128 v193, v[4:7] offset:33792
	v_lshl_add_u64 v[4:5], s[8:9], 0, v[136:137]
	v_lshlrev_b64 v[4:5], 11, v[4:5]
	v_lshl_add_u64 v[4:5], v[146:147], 0, v[4:5]
	global_load_dwordx4 v[4:7], v[4:5], off
	ds_read_b128 v[202:205], v192 offset:64
	ds_read_b128 v[206:209], v192 offset:8512
	v_cvt_pk_bf16_f32 v210, v96, v97
	v_cvt_pk_bf16_f32 v211, v98, v99
	v_cvt_pk_bf16_f32 v212, v100, v101
	v_cvt_pk_bf16_f32 v213, v102, v103
	s_waitcnt lgkmcnt(1)
	s_nop 0
	v_mfma_f32_16x16x32_bf16 v[164:167], v[202:205], v[210:213], v[164:167]
	ds_read_b128 v[202:205], v192 offset:16960
	s_waitcnt lgkmcnt(1)
	v_mfma_f32_16x16x32_bf16 v[168:171], v[206:209], v[210:213], v[168:171]
	ds_read_b128 v[206:209], v192 offset:25408
	s_waitcnt lgkmcnt(1)
	v_mfma_f32_16x16x32_bf16 v[176:179], v[202:205], v[210:213], v[176:179]
	s_waitcnt lgkmcnt(0)
	v_mfma_f32_16x16x32_bf16 v[172:175], v[206:209], v[210:213], v[172:175]
	s_waitcnt vmcnt(21)
	ds_write_b128 v194, v[8:11] offset:33792
	v_lshl_add_u64 v[8:9], s[8:9], 0, v[138:139]
	v_lshlrev_b64 v[8:9], 11, v[8:9]
	v_lshl_add_u64 v[8:9], v[146:147], 0, v[8:9]
	global_load_dwordx4 v[8:11], v[8:9], off
	ds_read_b128 v[202:205], v192 offset:128
	ds_read_b128 v[206:209], v192 offset:8576
	v_cvt_pk_bf16_f32 v210, v104, v105
	v_cvt_pk_bf16_f32 v211, v106, v107
	v_cvt_pk_bf16_f32 v212, v116, v117
	v_cvt_pk_bf16_f32 v213, v118, v119
	s_waitcnt lgkmcnt(1)
	s_nop 0
	v_mfma_f32_16x16x32_bf16 v[164:167], v[202:205], v[210:213], v[164:167]
	ds_read_b128 v[202:205], v192 offset:17024
	s_waitcnt lgkmcnt(1)
	v_mfma_f32_16x16x32_bf16 v[168:171], v[206:209], v[210:213], v[168:171]
	ds_read_b128 v[206:209], v192 offset:25472
	s_waitcnt lgkmcnt(1)
	v_mfma_f32_16x16x32_bf16 v[176:179], v[202:205], v[210:213], v[176:179]
	s_waitcnt lgkmcnt(0)
	v_mfma_f32_16x16x32_bf16 v[172:175], v[206:209], v[210:213], v[172:175]
	s_waitcnt vmcnt(21)
	ds_write_b128 v195, v[12:15] offset:33792
	v_lshl_add_u64 v[12:13], s[8:9], 0, v[140:141]
	v_lshlrev_b64 v[12:13], 11, v[12:13]
	v_lshl_add_u64 v[12:13], v[146:147], 0, v[12:13]
	global_load_dwordx4 v[12:15], v[12:13], off
	ds_read_b128 v[202:205], v192 offset:192
	ds_read_b128 v[206:209], v192 offset:8640
	v_cvt_pk_bf16_f32 v210, v108, v109
	v_cvt_pk_bf16_f32 v211, v110, v111
	v_cvt_pk_bf16_f32 v212, v112, v113
	v_cvt_pk_bf16_f32 v213, v114, v115
	s_min_u32 s20, s27, 60
	s_lshl_b32 s8, s20, 6
	s_waitcnt lgkmcnt(1)
	v_mfma_f32_16x16x32_bf16 v[164:167], v[202:205], v[210:213], v[164:167]
	ds_read_b128 v[202:205], v192 offset:17088
	s_addk_i32 s8, 0xc0
	s_lshl_b32 s20, s20, 13
	s_waitcnt lgkmcnt(1)
	v_mfma_f32_16x16x32_bf16 v[168:171], v[206:209], v[210:213], v[168:171]
	ds_read_b128 v[206:209], v192 offset:25536
	s_nop 1
	ds_write2_b32 v196, v164, v165 offset1:68
	ds_write2_b32 v196, v166, v167 offset0:136 offset1:204
	s_add_u32 s20, s12, s20
	s_waitcnt lgkmcnt(2)
	v_mfma_f32_16x16x32_bf16 v[164:167], v[206:209], v[210:213], v[172:175]
	v_add_u32_e32 v206, 0x3200, v196
	v_add_u32_e32 v207, 0x3400, v196
	s_addc_u32 s21, s13, 0
	v_mfma_f32_16x16x32_bf16 v[176:179], v[202:205], v[210:213], v[176:179]
	s_nop 3
	ds_write2_b32 v206, v164, v165 offset0:64 offset1:132
	v_lshl_add_u64 v[164:165], s[8:9], 0, v[128:129]
	v_add_u32_e32 v205, 0x2400, v196
	ds_write2_b32 v207, v166, v167 offset0:72 offset1:140
	v_lshlrev_b64 v[164:165], 12, v[164:165]
	v_lshl_add_u64 v[166:167], v[144:145], 1, s[20:21]
	v_add_u32_e32 v202, 0x1000, v196
	v_add_u32_e32 v203, 0x1200, v196
	v_add_u32_e32 v204, 0x2000, v196
	ds_write2_b32 v205, v178, v179 offset0:8 offset1:76
	v_lshl_add_u64 v[164:165], v[152:153], 0, v[164:165]
	v_lshl_add_u64 v[178:179], v[166:167], 0, v[130:131]
	ds_write2_b32 v202, v168, v169 offset0:64 offset1:132
	ds_write2_b32 v203, v170, v171 offset0:72 offset1:140
	ds_write2_b32 v204, v176, v177 offset0:128 offset1:196
	s_waitcnt lgkmcnt(0)
	s_barrier
	v_add_u32_e32 v208, v186, v180
	s_waitcnt vmcnt(20)
	ds_write_b128 v208, v[16:19]
	v_lshl_add_u64 v[16:17], s[8:9], 0, v[134:135]
	v_lshlrev_b64 v[166:167], 11, v[16:17]
	v_lshl_add_u64 v[16:17], v[132:133], 0, v[166:167]
	global_load_dwordx4 v[16:19], v[16:17], off
	ds_read_b64_tr_b16 v[236:237], v197 offset:33792
	ds_read_b64_tr_b16 v[238:239], v197 offset:35968
	ds_read_b64_tr_b16 v[240:241], v197 offset:51200
	ds_read_b64_tr_b16 v[242:243], v197 offset:53376
	v_add_u32_e32 v209, v186, v181
	s_waitcnt vmcnt(20)
	ds_write_b128 v209, v[20:23]
	v_lshl_add_u64 v[20:21], s[8:9], 0, v[136:137]
	v_lshlrev_b64 v[172:173], 11, v[20:21]
	v_lshl_add_u64 v[20:21], v[132:133], 0, v[172:173]
	global_load_dwordx4 v[20:23], v[20:21], off
	ds_read_b64_tr_b16 v[244:245], v197 offset:33824
	ds_read_b64_tr_b16 v[246:247], v197 offset:36000
	ds_read_b64_tr_b16 v[248:249], v197 offset:51232
	ds_read_b64_tr_b16 v[250:251], v197 offset:53408
	v_mov_b32_e32 v149, v148
	v_pk_mul_f32 v[90:91], v[148:149], v[90:91]
	v_pk_mul_f32 v[88:89], v[154:155], v[88:89]
	s_waitcnt lgkmcnt(5)
	s_nop 0
	v_mfma_f32_16x16x32_bf16 v[88:91], v[236:239], v[124:127], v[88:91]
	v_mfma_f32_16x16x32_bf16 v[88:91], v[240:243], v[120:123], v[88:91]
	v_add_u32_e32 v210, v186, v182
	s_waitcnt vmcnt(20)
	ds_write_b128 v210, v[24:27]
	v_lshl_add_u64 v[24:25], s[8:9], 0, v[138:139]
	v_lshlrev_b64 v[170:171], 11, v[24:25]
	v_lshl_add_u64 v[24:25], v[132:133], 0, v[170:171]
	global_load_dwordx4 v[24:27], v[24:25], off
	ds_read_b64_tr_b16 v[236:237], v197 offset:33856
	ds_read_b64_tr_b16 v[238:239], v197 offset:36032
	ds_read_b64_tr_b16 v[240:241], v197 offset:51264
	ds_read_b64_tr_b16 v[242:243], v197 offset:53440
	v_pk_mul_f32 v[94:95], v[148:149], v[94:95]
	v_pk_mul_f32 v[92:93], v[154:155], v[92:93]
	s_waitcnt lgkmcnt(5)
	s_nop 0
	v_mfma_f32_16x16x32_bf16 v[92:95], v[244:247], v[124:127], v[92:95]
	v_mfma_f32_16x16x32_bf16 v[92:95], v[248:251], v[120:123], v[92:95]
	v_add_u32_e32 v211, v186, v183
	s_waitcnt vmcnt(20)
	ds_write_b128 v211, v[28:31]
	v_lshl_add_u64 v[28:29], s[8:9], 0, v[140:141]
	v_lshlrev_b64 v[168:169], 11, v[28:29]
	v_lshl_add_u64 v[28:29], v[132:133], 0, v[168:169]
	global_load_dwordx4 v[28:31], v[28:29], off
	ds_read_b64_tr_b16 v[244:245], v197 offset:33888
	ds_read_b64_tr_b16 v[246:247], v197 offset:36064
	ds_read_b64_tr_b16 v[248:249], v197 offset:51296
	ds_read_b64_tr_b16 v[250:251], v197 offset:53472
	v_pk_mul_f32 v[98:99], v[148:149], v[98:99]
	v_pk_mul_f32 v[96:97], v[154:155], v[96:97]
	s_waitcnt lgkmcnt(5)
	s_nop 0
	v_mfma_f32_16x16x32_bf16 v[96:99], v[236:239], v[124:127], v[96:99]
	v_mfma_f32_16x16x32_bf16 v[96:99], v[240:243], v[120:123], v[96:99]
	s_waitcnt vmcnt(20)
	ds_write_b128 v184, v[36:39]
	global_load_dwordx4 v[36:39], v[164:165], off
	ds_read_b64_tr_b16 v[236:237], v198 offset:33792
	ds_read_b64_tr_b16 v[238:239], v198 offset:35968
	ds_read_b64_tr_b16 v[240:241], v198 offset:51200
	ds_read_b64_tr_b16 v[242:243], v198 offset:53376
	v_pk_mul_f32 v[102:103], v[148:149], v[102:103]
	v_pk_mul_f32 v[100:101], v[154:155], v[100:101]
	s_waitcnt lgkmcnt(5)
	s_nop 0
	v_mfma_f32_16x16x32_bf16 v[100:103], v[244:247], v[124:127], v[100:103]
	v_mfma_f32_16x16x32_bf16 v[100:103], v[248:251], v[120:123], v[100:103]
	v_pk_mul_f32 v[106:107], v[148:149], v[106:107]
	v_pk_mul_f32 v[104:105], v[154:155], v[104:105]
	s_waitcnt lgkmcnt(0)
	s_nop 0
	v_mfma_f32_16x16x32_bf16 v[104:107], v[236:239], v[124:127], v[104:107]
	v_mfma_f32_16x16x32_bf16 v[104:107], v[240:243], v[120:123], v[104:107]
	s_waitcnt vmcnt(20)
	ds_write_b128 v185, v[40:43]
	v_add_co_u32_e32 v40, vcc, s23, v178
	s_nop 1
	v_addc_co_u32_e32 v41, vcc, 0, v179, vcc
	global_load_dwordx4 v[40:43], v[40:41], off
	ds_read_b64_tr_b16 v[174:175], v199 offset:33792
	ds_read_b64_tr_b16 v[176:177], v199 offset:35968
	ds_read_b64_tr_b16 v[212:213], v199 offset:51200
	ds_read_b64_tr_b16 v[214:215], v199 offset:53376
	v_pk_mul_f32 v[118:119], v[148:149], v[118:119]
	v_pk_mul_f32 v[116:117], v[154:155], v[116:117]
	v_pk_mul_f32 v[110:111], v[148:149], v[110:111]
	v_pk_mul_f32 v[108:109], v[154:155], v[108:109]
	s_waitcnt lgkmcnt(2)
	v_mfma_f32_16x16x32_bf16 v[116:119], v[174:177], v[124:127], v[116:119]
	ds_read_b64_tr_b16 v[174:175], v200 offset:33792
	ds_read_b64_tr_b16 v[176:177], v200 offset:35968
	v_pk_mul_f32 v[114:115], v[148:149], v[114:115]
	v_pk_mul_f32 v[112:113], v[154:155], v[112:113]
	s_waitcnt lgkmcnt(2)
	v_mfma_f32_16x16x32_bf16 v[116:119], v[212:215], v[120:123], v[116:119]
	ds_read_b64_tr_b16 v[212:213], v200 offset:51200
	ds_read_b64_tr_b16 v[214:215], v200 offset:53376
	s_waitcnt lgkmcnt(2)
	v_mfma_f32_16x16x32_bf16 v[108:111], v[174:177], v[124:127], v[108:111]
	s_waitcnt lgkmcnt(0)
	v_mfma_f32_16x16x32_bf16 v[108:111], v[212:215], v[120:123], v[108:111]
	ds_read_b128 v[174:177], v188
	ds_read_b128 v[212:215], v188 offset:16
	ds_read_b128 v[216:219], v187
	ds_read_b128 v[220:223], v187 offset:16
	ds_read_b64_tr_b16 v[224:225], v201 offset:33792
	ds_read_b64_tr_b16 v[226:227], v201 offset:35968
	s_waitcnt lgkmcnt(3)
	v_pk_add_f32 v[164:165], v[176:177], v[218:219]
	v_pk_add_f32 v[176:177], v[174:175], v[216:217]
	v_pk_mul_f32 v[174:175], v[156:157], v[164:165]
	v_pk_mul_f32 v[178:179], v[142:143], v[176:177]
	s_waitcnt lgkmcnt(2)
	v_pk_add_f32 v[176:177], v[212:213], v[220:221]
	v_mul_f32_e32 v212, v179, v179
	v_mul_f32_e32 v213, v175, v175
	v_pk_mul_f32 v[176:177], v[142:143], v[176:177]
	v_fmac_f32_e32 v212, v178, v178
	v_fmac_f32_e32 v213, v174, v174
	v_pk_add_f32 v[164:165], v[214:215], v[222:223]
	v_add_f32_e32 v212, v212, v213
	v_mul_f32_e32 v213, v177, v177
	v_pk_mul_f32 v[164:165], v[156:157], v[164:165]
	v_fmac_f32_e32 v213, v176, v176
	v_add_f32_e32 v212, v213, v212
	v_mul_f32_e32 v213, v165, v165
	v_fmac_f32_e32 v213, v164, v164
	v_add_f32_e32 v216, v213, v212
	ds_swizzle_b32 v217, v216 offset:swizzle(SWAP,1)
	s_waitcnt lgkmcnt(1)
	v_mfma_f32_16x16x32_bf16 v[112:115], v[224:227], v[124:127], v[112:115]
	ds_read_b64_tr_b16 v[212:213], v201 offset:51200
	ds_read_b64_tr_b16 v[214:215], v201 offset:53376
	s_waitcnt lgkmcnt(2)
	v_add_f32_e32 v124, v216, v217
	ds_swizzle_b32 v125, v124 offset:swizzle(SWAP,2)
	s_waitcnt lgkmcnt(1)
	v_mfma_f32_16x16x32_bf16 v[112:115], v[212:215], v[120:123], v[112:115]
	s_waitcnt lgkmcnt(0)
	v_add_f32_e32 v124, v124, v125
	ds_swizzle_b32 v125, v124 offset:swizzle(SWAP,4)
	s_and_saveexec_b64 s[20:21], s[6:7]
	s_cbranch_execz .LBB0_619
	v_lshl_add_u64 v[120:121], s[14:15], 0, v[160:161]
	v_add_co_u32_e32 v120, vcc, 0x4200000, v120
	s_waitcnt lgkmcnt(0)
	v_add_f32_e32 v122, v124, v125
	v_addc_co_u32_e32 v121, vcc, 0, v121, vcc
	global_store_dword v[120:121], v122, off
.LBB0_619:
	s_or_b64 exec, exec, s[20:21]
	v_lshlrev_b32_e32 v120, 16, v32
	v_and_b32_e32 v121, 0xffff0000, v32
	v_pk_mul_f32 v[120:121], v[178:179], v[120:121]
	s_add_i32 s8, s22, -1
	v_cvt_pk_bf16_f32 v32, v120, v121
	v_lshlrev_b32_e32 v120, 16, v33
	v_and_b32_e32 v121, 0xffff0000, v33
	v_pk_mul_f32 v[120:121], v[174:175], v[120:121]
	s_cmp_lt_u32 s27, 62
	v_cvt_pk_bf16_f32 v33, v120, v121
	v_lshlrev_b32_e32 v120, 16, v34
	v_and_b32_e32 v121, 0xffff0000, v34
	v_pk_mul_f32 v[120:121], v[176:177], v[120:121]
	s_cselect_b32 s8, s8, s27
	v_cvt_pk_bf16_f32 v34, v120, v121
	v_lshlrev_b32_e32 v120, 16, v35
	v_and_b32_e32 v121, 0xffff0000, v35
	v_pk_mul_f32 v[120:121], v[164:165], v[120:121]
	v_lshl_add_u64 v[164:165], s[14:15], 0, v[162:163]
	v_cvt_pk_bf16_f32 v35, v120, v121
	v_add_co_u32_e32 v120, vcc, s24, v164
	s_lshl_b32 s8, s8, 6
	s_nop 0
	v_addc_co_u32_e32 v121, vcc, 0, v165, vcc
	global_store_dwordx4 v[120:121], v[32:35], off
	s_nop 1
	v_lshl_add_u64 v[32:33], s[8:9], 0, v[128:129]
	v_lshlrev_b64 v[32:33], 12, v[32:33]
	v_lshl_add_u64 v[32:33], v[158:159], 0, v[32:33]
	global_load_dwordx4 v[32:35], v[32:33], off
	s_waitcnt lgkmcnt(0)
	s_barrier
	ds_read_b128 v[174:177], v190
	ds_read_b64_tr_b16 v[126:127], v189 offset:576
	ds_read_b64_tr_b16 v[122:123], v189 offset:5184
	ds_read_b64_tr_b16 v[124:125], v189
	ds_read_b64_tr_b16 v[120:121], v189 offset:4608
	ds_read_b128 v[212:215], v190 offset:2304
	ds_read_b128 v[220:223], v190 offset:4608
	ds_read_b128 v[224:227], v190 offset:6912
	s_waitcnt lgkmcnt(5)
	v_cndmask_b32_e64 v219, v123, v127, s[4:5]
	v_cndmask_b32_e64 v218, v122, v126, s[4:5]
	s_waitcnt lgkmcnt(3)
	v_cndmask_b32_e64 v217, v121, v125, s[4:5]
	v_cndmask_b32_e64 v216, v120, v124, s[4:5]
	s_nop 1
	v_mfma_f32_16x16x32_bf16 v[174:177], v[174:177], v[216:219], 0
	s_waitcnt lgkmcnt(2)
	v_mfma_f32_16x16x32_bf16 v[212:215], v[212:215], v[216:219], 0
	s_waitcnt lgkmcnt(1)
	v_mfma_f32_16x16x32_bf16 v[220:223], v[220:223], v[216:219], 0
	s_waitcnt lgkmcnt(0)
	v_mfma_f32_16x16x32_bf16 v[216:219], v[224:227], v[216:219], 0
	s_waitcnt vmcnt(22)
	ds_write_b128 v191, v[44:47] offset:33792
	v_lshl_add_u64 v[44:45], v[146:147], 0, v[166:167]
	global_load_dwordx4 v[44:47], v[44:45], off
	ds_read_b128 v[224:227], v192
	ds_read_b128 v[228:231], v192 offset:8448
	v_cvt_pk_bf16_f32 v232, v88, v89
	v_cvt_pk_bf16_f32 v233, v90, v91
	v_cvt_pk_bf16_f32 v234, v92, v93
	v_cvt_pk_bf16_f32 v235, v94, v95
	s_waitcnt lgkmcnt(1)
	s_nop 0
	v_mfma_f32_16x16x32_bf16 v[174:177], v[224:227], v[232:235], v[174:177]
	ds_read_b128 v[224:227], v192 offset:16896
	s_waitcnt lgkmcnt(1)
	v_mfma_f32_16x16x32_bf16 v[212:215], v[228:231], v[232:235], v[212:215]
	ds_read_b128 v[228:231], v192 offset:25344
	s_waitcnt lgkmcnt(1)
	v_mfma_f32_16x16x32_bf16 v[220:223], v[224:227], v[232:235], v[220:223]
	s_waitcnt lgkmcnt(0)
	v_mfma_f32_16x16x32_bf16 v[216:219], v[228:231], v[232:235], v[216:219]
	s_waitcnt vmcnt(22)
	ds_write_b128 v193, v[48:51] offset:33792
	v_lshl_add_u64 v[48:49], v[146:147], 0, v[172:173]
	global_load_dwordx4 v[48:51], v[48:49], off
	ds_read_b128 v[224:227], v192 offset:64
	ds_read_b128 v[228:231], v192 offset:8512
	v_cvt_pk_bf16_f32 v232, v96, v97
	v_cvt_pk_bf16_f32 v233, v98, v99
	v_cvt_pk_bf16_f32 v234, v100, v101
	v_cvt_pk_bf16_f32 v235, v102, v103
	s_waitcnt lgkmcnt(1)
	s_nop 0
	v_mfma_f32_16x16x32_bf16 v[172:175], v[224:227], v[232:235], v[174:177]
	ds_read_b128 v[224:227], v192 offset:25408
	s_nop 1
	ds_read_b128 v[176:179], v192 offset:16960
	s_waitcnt lgkmcnt(2)
	v_mfma_f32_16x16x32_bf16 v[212:215], v[228:231], v[232:235], v[212:215]
	s_waitcnt lgkmcnt(0)
	v_mfma_f32_16x16x32_bf16 v[176:179], v[176:179], v[232:235], v[220:223]
	v_mfma_f32_16x16x32_bf16 v[216:219], v[224:227], v[232:235], v[216:219]
	s_waitcnt vmcnt(22)
	ds_write_b128 v194, v[52:55] offset:33792
	v_lshl_add_u64 v[52:53], v[146:147], 0, v[170:171]
	global_load_dwordx4 v[52:55], v[52:53], off
	ds_read_b128 v[220:223], v192 offset:128
	ds_read_b128 v[224:227], v192 offset:8576
	v_cvt_pk_bf16_f32 v228, v104, v105
	v_cvt_pk_bf16_f32 v229, v106, v107
	v_cvt_pk_bf16_f32 v230, v116, v117
	v_cvt_pk_bf16_f32 v231, v118, v119
	s_waitcnt lgkmcnt(1)
	s_nop 0
	v_mfma_f32_16x16x32_bf16 v[170:173], v[220:223], v[228:231], v[172:175]
	ds_read_b128 v[220:223], v192 offset:17024
	s_waitcnt lgkmcnt(1)
	v_mfma_f32_16x16x32_bf16 v[212:215], v[224:227], v[228:231], v[212:215]
	ds_read_b128 v[224:227], v192 offset:25472
	s_waitcnt lgkmcnt(1)
	v_mfma_f32_16x16x32_bf16 v[174:177], v[220:223], v[228:231], v[176:179]
	s_waitcnt lgkmcnt(0)
	v_mfma_f32_16x16x32_bf16 v[216:219], v[224:227], v[228:231], v[216:219]
	s_waitcnt vmcnt(22)
	ds_write_b128 v195, v[56:59] offset:33792
	v_lshl_add_u64 v[56:57], v[146:147], 0, v[168:169]
	global_load_dwordx4 v[56:59], v[56:57], off
	ds_read_b128 v[166:169], v192 offset:192
	ds_read_b128 v[220:223], v192 offset:8640
	v_cvt_pk_bf16_f32 v224, v108, v109
	v_cvt_pk_bf16_f32 v225, v110, v111
	v_cvt_pk_bf16_f32 v226, v112, v113
	v_cvt_pk_bf16_f32 v227, v114, v115
	s_min_u32 s20, s27, 59
	s_lshl_b32 s8, s20, 6
	s_waitcnt lgkmcnt(1)
	v_mfma_f32_16x16x32_bf16 v[166:169], v[166:169], v[224:227], v[170:173]
	s_addk_i32 s8, 0x100
	s_lshl_b32 s20, s20, 13
	s_add_u32 s20, s12, s20
	ds_read_b128 v[170:173], v192 offset:17088
	s_waitcnt lgkmcnt(1)
	v_mfma_f32_16x16x32_bf16 v[212:215], v[220:223], v[224:227], v[212:215]
	ds_read_b128 v[220:223], v192 offset:25536
	s_nop 0
	ds_write2_b32 v196, v166, v167 offset1:68
	ds_write2_b32 v196, v168, v169 offset0:136 offset1:204
	s_nop 3
	ds_write2_b32 v202, v212, v213 offset0:64 offset1:132
	s_addc_u32 s21, s13, 0
	s_waitcnt lgkmcnt(4)
	v_mfma_f32_16x16x32_bf16 v[170:173], v[170:173], v[224:227], v[174:177]
	s_waitcnt lgkmcnt(3)
	v_mfma_f32_16x16x32_bf16 v[166:169], v[220:223], v[224:227], v[216:219]
	ds_write2_b32 v203, v214, v215 offset0:72 offset1:140
	s_nop 4
	ds_write2_b32 v204, v170, v171 offset0:128 offset1:196
	ds_write2_b32 v205, v172, v173 offset0:8 offset1:76
	ds_write2_b32 v206, v166, v167 offset0:64 offset1:132
	ds_write2_b32 v207, v168, v169 offset0:72 offset1:140
	v_lshl_add_u64 v[166:167], s[8:9], 0, v[128:129]
	v_lshlrev_b64 v[166:167], 12, v[166:167]
	v_lshl_add_u64 v[174:175], v[152:153], 0, v[166:167]
	v_lshl_add_u64 v[166:167], v[144:145], 1, s[20:21]
	s_waitcnt lgkmcnt(0)
	s_barrier
	v_lshl_add_u64 v[176:177], v[166:167], 0, v[130:131]
	s_waitcnt vmcnt(21)
	ds_write_b128 v208, v[60:63]
	v_lshl_add_u64 v[60:61], s[8:9], 0, v[134:135]
	v_lshlrev_b64 v[60:61], 11, v[60:61]
	v_lshl_add_u64 v[60:61], v[132:133], 0, v[60:61]
	global_load_dwordx4 v[60:63], v[60:61], off
	ds_read_b64_tr_b16 v[236:237], v197 offset:33792
	ds_read_b64_tr_b16 v[238:239], v197 offset:35968
	ds_read_b64_tr_b16 v[240:241], v197 offset:51200
	ds_read_b64_tr_b16 v[242:243], v197 offset:53376
	s_waitcnt vmcnt(21)
	ds_write_b128 v209, v[64:67]
	v_lshl_add_u64 v[64:65], s[8:9], 0, v[136:137]
	v_lshlrev_b64 v[64:65], 11, v[64:65]
	v_lshl_add_u64 v[64:65], v[132:133], 0, v[64:65]
	global_load_dwordx4 v[64:67], v[64:65], off
	ds_read_b64_tr_b16 v[244:245], v197 offset:33824
	ds_read_b64_tr_b16 v[246:247], v197 offset:36000
	ds_read_b64_tr_b16 v[248:249], v197 offset:51232
	ds_read_b64_tr_b16 v[250:251], v197 offset:53408
	v_pk_mul_f32 v[90:91], v[148:149], v[90:91]
	v_pk_mul_f32 v[88:89], v[154:155], v[88:89]
	s_waitcnt lgkmcnt(5)
	s_nop 0
	v_mfma_f32_16x16x32_bf16 v[88:91], v[236:239], v[124:127], v[88:91]
	v_mfma_f32_16x16x32_bf16 v[88:91], v[240:243], v[120:123], v[88:91]
	s_waitcnt vmcnt(21)
	ds_write_b128 v210, v[68:71]
	v_lshl_add_u64 v[68:69], s[8:9], 0, v[138:139]
	v_lshlrev_b64 v[68:69], 11, v[68:69]
	v_lshl_add_u64 v[68:69], v[132:133], 0, v[68:69]
	global_load_dwordx4 v[68:71], v[68:69], off
	ds_read_b64_tr_b16 v[236:237], v197 offset:33856
	ds_read_b64_tr_b16 v[238:239], v197 offset:36032
	ds_read_b64_tr_b16 v[240:241], v197 offset:51264
	ds_read_b64_tr_b16 v[242:243], v197 offset:53440
	v_pk_mul_f32 v[94:95], v[148:149], v[94:95]
	v_pk_mul_f32 v[92:93], v[154:155], v[92:93]
	s_waitcnt lgkmcnt(5)
	s_nop 0
	v_mfma_f32_16x16x32_bf16 v[92:95], v[244:247], v[124:127], v[92:95]
	v_mfma_f32_16x16x32_bf16 v[92:95], v[248:251], v[120:123], v[92:95]
	s_waitcnt vmcnt(21)
	ds_write_b128 v211, v[76:79]
	v_lshl_add_u64 v[76:77], s[8:9], 0, v[140:141]
	v_lshlrev_b64 v[76:77], 11, v[76:77]
	v_lshl_add_u64 v[76:77], v[132:133], 0, v[76:77]
	global_load_dwordx4 v[76:79], v[76:77], off
	ds_read_b64_tr_b16 v[244:245], v197 offset:33888
	ds_read_b64_tr_b16 v[246:247], v197 offset:36064
	ds_read_b64_tr_b16 v[248:249], v197 offset:51296
	ds_read_b64_tr_b16 v[250:251], v197 offset:53472
	v_pk_mul_f32 v[98:99], v[148:149], v[98:99]
	v_pk_mul_f32 v[96:97], v[154:155], v[96:97]
	s_waitcnt lgkmcnt(5)
	s_nop 0
	v_mfma_f32_16x16x32_bf16 v[96:99], v[236:239], v[124:127], v[96:99]
	v_mfma_f32_16x16x32_bf16 v[96:99], v[240:243], v[120:123], v[96:99]
	s_waitcnt vmcnt(21)
	ds_write_b128 v184, v[80:83]
	global_load_dwordx4 v[80:83], v[174:175], off
	ds_read_b64_tr_b16 v[236:237], v198 offset:33792
	ds_read_b64_tr_b16 v[238:239], v198 offset:35968
	ds_read_b64_tr_b16 v[240:241], v198 offset:51200
	ds_read_b64_tr_b16 v[242:243], v198 offset:53376
	v_pk_mul_f32 v[102:103], v[148:149], v[102:103]
	v_pk_mul_f32 v[100:101], v[154:155], v[100:101]
	s_waitcnt lgkmcnt(5)
	s_nop 0
	v_mfma_f32_16x16x32_bf16 v[100:103], v[244:247], v[124:127], v[100:103]
	v_mfma_f32_16x16x32_bf16 v[100:103], v[248:251], v[120:123], v[100:103]
	v_pk_mul_f32 v[106:107], v[148:149], v[106:107]
	v_pk_mul_f32 v[104:105], v[154:155], v[104:105]
	s_waitcnt lgkmcnt(0)
	s_nop 0
	v_mfma_f32_16x16x32_bf16 v[104:107], v[236:239], v[124:127], v[104:107]
	v_mfma_f32_16x16x32_bf16 v[104:107], v[240:243], v[120:123], v[104:107]
	s_waitcnt vmcnt(21)
	ds_write_b128 v185, v[84:87]
	v_add_co_u32_e32 v84, vcc, s25, v176
	s_nop 1
	v_addc_co_u32_e32 v85, vcc, 0, v177, vcc
	global_load_dwordx4 v[84:87], v[84:85], off
	ds_read_b64_tr_b16 v[166:167], v199 offset:33792
	ds_read_b64_tr_b16 v[168:169], v199 offset:35968
	ds_read_b64_tr_b16 v[170:171], v199 offset:51200
	ds_read_b64_tr_b16 v[172:173], v199 offset:53376
	v_pk_mul_f32 v[118:119], v[148:149], v[118:119]
	v_pk_mul_f32 v[116:117], v[154:155], v[116:117]
	v_pk_mul_f32 v[110:111], v[148:149], v[110:111]
	v_pk_mul_f32 v[108:109], v[154:155], v[108:109]
	s_waitcnt lgkmcnt(2)
	v_mfma_f32_16x16x32_bf16 v[116:119], v[166:169], v[124:127], v[116:119]
	ds_read_b64_tr_b16 v[166:167], v200 offset:33792
	ds_read_b64_tr_b16 v[168:169], v200 offset:35968
	v_pk_mul_f32 v[114:115], v[148:149], v[114:115]
	v_pk_mul_f32 v[112:113], v[154:155], v[112:113]
	s_waitcnt lgkmcnt(2)
	v_mfma_f32_16x16x32_bf16 v[116:119], v[170:173], v[120:123], v[116:119]
	ds_read_b64_tr_b16 v[170:171], v200 offset:51200
	ds_read_b64_tr_b16 v[172:173], v200 offset:53376
	s_waitcnt lgkmcnt(2)
	v_mfma_f32_16x16x32_bf16 v[108:111], v[166:169], v[124:127], v[108:111]
	s_waitcnt lgkmcnt(0)
	v_mfma_f32_16x16x32_bf16 v[108:111], v[170:173], v[120:123], v[108:111]
	ds_read_b128 v[166:169], v188
	ds_read_b128 v[174:177], v188 offset:16
	ds_read_b128 v[170:173], v187
	ds_read_b128 v[202:205], v187 offset:16
	ds_read_b64_tr_b16 v[206:207], v201 offset:33792
	ds_read_b64_tr_b16 v[208:209], v201 offset:35968
	s_waitcnt lgkmcnt(3)
	v_pk_add_f32 v[168:169], v[168:169], v[172:173]
	v_pk_add_f32 v[166:167], v[166:167], v[170:171]
	v_pk_mul_f32 v[168:169], v[156:157], v[168:169]
	v_pk_mul_f32 v[172:173], v[142:143], v[166:167]
	s_waitcnt lgkmcnt(2)
	v_pk_add_f32 v[170:171], v[174:175], v[202:203]
	v_mul_f32_e32 v149, v173, v173
	v_mul_f32_e32 v174, v169, v169
	v_pk_mul_f32 v[170:171], v[142:143], v[170:171]
	v_fmac_f32_e32 v149, v172, v172
	v_fmac_f32_e32 v174, v168, v168
	v_pk_add_f32 v[166:167], v[176:177], v[204:205]
	v_add_f32_e32 v149, v149, v174
	v_mul_f32_e32 v174, v171, v171
	v_pk_mul_f32 v[166:167], v[156:157], v[166:167]
	v_fmac_f32_e32 v174, v170, v170
	v_add_f32_e32 v149, v174, v149
	v_mul_f32_e32 v174, v167, v167
	v_fmac_f32_e32 v174, v166, v166
	v_add_f32_e32 v149, v174, v149
	ds_swizzle_b32 v178, v149 offset:swizzle(SWAP,1)
	s_waitcnt lgkmcnt(1)
	v_mfma_f32_16x16x32_bf16 v[112:115], v[206:209], v[124:127], v[112:115]
	ds_read_b64_tr_b16 v[174:175], v201 offset:51200
	ds_read_b64_tr_b16 v[176:177], v201 offset:53376
	s_waitcnt lgkmcnt(2)
	v_add_f32_e32 v124, v149, v178
	ds_swizzle_b32 v125, v124 offset:swizzle(SWAP,2)
	s_waitcnt lgkmcnt(1)
	v_mfma_f32_16x16x32_bf16 v[112:115], v[174:177], v[120:123], v[112:115]
	s_waitcnt lgkmcnt(0)
	v_add_f32_e32 v124, v124, v125
	ds_swizzle_b32 v125, v124 offset:swizzle(SWAP,4)
	s_and_saveexec_b64 s[20:21], s[6:7]
	s_cbranch_execz .LBB0_616
	v_lshl_add_u64 v[120:121], s[14:15], 0, v[160:161]
	v_add_co_u32_e32 v120, vcc, 0x4202000, v120
	s_waitcnt lgkmcnt(0)
	v_add_f32_e32 v122, v124, v125
	v_addc_co_u32_e32 v121, vcc, 0, v121, vcc
	global_store_dword v[120:121], v122, off
	s_branch .LBB0_616
